# finalize_rows: the per-layer lambda (128 parameter loads + dot products + 2 exp) is computed once per block and reused for its remaining items instead of being recomputed for every item
# speedup vs baseline: 1.0062x; 1.0062x over previous
.LBB0_199:
	s_and_b64 vcc, exec, s[0:1]
	s_cbranch_vccz .LBB0_210
	v_readlane_b32 s0, v243, 6
	s_cmp_lg_u32 s0, 0
	s_cbranch_scc0 .LBB0_205
	v_readlane_b32 s0, v245, 48
	v_readlane_b32 s1, v245, 49
	s_andn2_b64 vcc, exec, s[0:1]
	v_readlane_b32 s40, v247, 41
	v_readlane_b32 s0, v246, 9
	v_readlane_b32 s24, v247, 5
	v_readlane_b32 s41, v247, 42
	v_readlane_b32 s42, v247, 43
	v_readlane_b32 s43, v247, 44
	v_readlane_b32 s44, v247, 45
	v_readlane_b32 s45, v247, 46
	v_readlane_b32 s46, v247, 47
	v_readlane_b32 s47, v247, 48
	v_readlane_b32 s48, v247, 49
	v_readlane_b32 s49, v247, 50
	v_readlane_b32 s50, v247, 51
	v_readlane_b32 s51, v247, 52
	v_readlane_b32 s52, v247, 53
	v_readlane_b32 s53, v247, 54
	v_readlane_b32 s54, v247, 55
	v_readlane_b32 s55, v247, 56
	v_readlane_b32 s14, v246, 23
	v_readlane_b32 s15, v246, 24
	s_movk_i32 s16, 0x1000
	s_mov_b32 s17, 0x3fb8aa3b
	s_mov_b32 s18, 0xc2ce8ed0
	s_mov_b32 s19, 0x42b17218
	s_movk_i32 s20, 0x1a00
	s_mov_b32 s21, 0x600000
	v_readlane_b32 s25, v247, 6
	v_readlane_b32 s26, v247, 7
	v_readlane_b32 s27, v247, 8
	v_readlane_b32 s1, v246, 10
	v_readlane_b32 s2, v246, 11
	v_readlane_b32 s3, v246, 12
	v_readlane_b32 s4, v246, 13
	v_readlane_b32 s5, v246, 14
	v_readlane_b32 s6, v246, 15
	v_readlane_b32 s7, v246, 16
	v_readlane_b32 s8, v246, 17
	v_readlane_b32 s9, v246, 18
	v_readlane_b32 s10, v246, 19
	v_readlane_b32 s11, v246, 20
	v_readlane_b32 s12, v246, 21
	v_readlane_b32 s13, v246, 22
	s_cbranch_vccnz .LBB0_204
	v_readlane_b32 s0, v243, 31
	s_mov_b32 s4, s0
	v_cvt_f32_i32_e32 v0, s4
	v_readlane_b32 s1, v243, 32
	s_lshl_b32 s0, s0, 7
	s_mov_b64 s[66:67], s[54:55]
	v_mul_f32_e32 v0, 0xbe99999a, v0
	v_mul_f32_e32 v1, 0x3fb8aa3b, v0
	v_fma_f32 v2, v0, s17, -v1
	v_rndne_f32_e32 v3, v1
	s_ashr_i32 s1, s0, 31
	s_lshl_b32 s2, s4, 6
	s_lshl_b32 s6, s4, 8
	s_mov_b64 s[64:65], s[52:53]
	s_mov_b64 s[62:63], s[50:51]
	s_mov_b64 s[60:61], s[48:49]
	s_mov_b64 s[58:59], s[46:47]
	s_mov_b64 s[56:57], s[44:45]
	s_mov_b64 s[54:55], s[42:43]
	s_mov_b64 s[52:53], s[40:41]
	v_readlane_b32 s36, v247, 9
	v_fmac_f32_e32 v2, 0x32a5705f, v0
	v_sub_f32_e32 v1, v1, v3
	s_ashr_i32 s3, s2, 31
	s_lshl_b32 s8, s4, 2
	s_ashr_i32 s7, s6, 31
	s_lshl_b64 s[0:1], s[0:1], 2
	v_readlane_b32 s46, v247, 19
	v_add_f32_e32 v1, v1, v2
	v_readlane_b32 s47, v247, 20
	s_add_u32 s0, s46, s0
	v_cvt_i32_f32_e32 v3, v3
	v_exp_f32_e32 v1, v1
	v_readlane_b32 s48, v247, 21
	s_addc_u32 s1, s47, s1
	s_lshl_b64 s[4:5], s[2:3], 2
	v_readlane_b32 s37, v247, 10
	v_readlane_b32 s38, v247, 11
	v_readlane_b32 s39, v247, 12
	v_readlane_b32 s40, v247, 13
	v_readlane_b32 s41, v247, 14
	v_readlane_b32 s42, v247, 15
	v_readlane_b32 s43, v247, 16
	v_readlane_b32 s44, v247, 17
	v_readlane_b32 s45, v247, 18
	v_readlane_b32 s49, v247, 22
	v_readlane_b32 s50, v247, 23
	v_readlane_b32 s51, v247, 24
	s_add_u32 s2, s48, s4
	s_addc_u32 s3, s49, s5
	v_readlane_b32 s36, v247, 25
	v_readlane_b32 s40, v247, 29
	v_ldexp_f32 v1, v1, v3
	v_cmp_ngt_f32_e32 vcc, s18, v0
	v_readlane_b32 s41, v247, 30
	v_readlane_b32 s42, v247, 31
	v_readlane_b32 s43, v247, 32
	v_readlane_b32 s44, v247, 33
	v_readlane_b32 s45, v247, 34
	v_readlane_b32 s46, v247, 35
	v_readlane_b32 s47, v247, 36
	v_readlane_b32 s48, v247, 37
	v_readlane_b32 s49, v247, 38
	v_readlane_b32 s50, v247, 39
	v_readlane_b32 s51, v247, 40
	s_add_u32 s4, s40, s4
	v_cndmask_b32_e32 v1, 0, v1, vcc
	v_cmp_nlt_f32_e32 vcc, s19, v0
	s_addc_u32 s5, s41, s5
	s_mov_b64 s[40:41], s[52:53]
	v_cndmask_b32_e32 v0, v185, v1, vcc
	s_mov_b64 s[50:51], s[62:63]
	s_lshl_b64 s[6:7], s[6:7], 2
	s_waitcnt vmcnt(9)
	v_fmamk_f32 v17, v0, 0xbf19999a, v171
	s_add_u32 s6, s50, s6
	v_sub_f32_e32 v22, 1.0, v17
	s_movk_i32 s36, 0x880
	s_mov_b64 s[48:49], s[60:61]
	s_addc_u32 s7, s51, s7
	s_lshl_b32 s9, s90, 2
	v_readlane_b32 s10, v244, 53
	v_readlane_b32 s11, v247, 0
	v_readlane_b32 s37, v247, 26
	v_readlane_b32 s38, v247, 27
	v_readlane_b32 s39, v247, 28
	s_mov_b64 s[42:43], s[54:55]
	s_mov_b64 s[44:45], s[56:57]
	s_mov_b64 s[46:47], s[58:59]
	s_mov_b64 s[52:53], s[64:65]
	s_mov_b64 s[54:55], s[66:67]
	s_mov_b32 s98, 0
.LBB0_203:
	s_cmp_lg_u32 s98, 0
	s_cbranch_scc1 fin_lam_skip
	v_mov_b32_e32 v16, v139
	global_load_dwordx4 v[4:7], v137, s[0:1] offset:48
	global_load_dwordx4 v[8:11], v137, s[0:1] offset:32
	global_load_dwordx4 v[12:15], v137, s[0:1] offset:16
	global_load_dwordx4 v[18:21], v137, s[0:1]
	global_load_dwordx4 v[24:27], v137, s[0:1] offset:176
	global_load_dwordx4 v[28:31], v137, s[0:1] offset:160
	global_load_dwordx4 v[32:35], v137, s[0:1] offset:144
	global_load_dwordx4 v[36:39], v137, s[0:1] offset:128
	global_load_dwordx4 v[40:43], v137, s[0:1] offset:304
	global_load_dwordx4 v[44:47], v137, s[0:1] offset:288
	global_load_dwordx4 v[48:51], v137, s[0:1] offset:272
	global_load_dwordx4 v[52:55], v137, s[0:1] offset:256
	global_load_dwordx4 v[56:59], v137, s[0:1] offset:432
	global_load_dwordx4 v[60:63], v137, s[0:1] offset:416
	global_load_dwordx4 v[64:67], v137, s[0:1] offset:400
	global_load_dwordx4 v[68:71], v137, s[0:1] offset:384
	v_ashrrev_i32_e32 v0, 6, v16
	v_readlane_b32 s52, v246, 25
	v_add_u32_e32 v0, s10, v0
	v_readlane_b32 s53, v246, 26
	v_readlane_b32 s54, v246, 27
	v_readlane_b32 s55, v246, 28
	v_readlane_b32 s56, v246, 29
	v_readlane_b32 s57, v246, 30
	v_readlane_b32 s58, v246, 31
	v_readlane_b32 s59, v246, 32
	v_readlane_b32 s60, v246, 33
	v_readlane_b32 s61, v246, 34
	v_readlane_b32 s62, v246, 35
	v_readlane_b32 s63, v246, 36
	v_readlane_b32 s64, v246, 37
	v_readlane_b32 s65, v246, 38
	v_readlane_b32 s66, v246, 39
	v_readlane_b32 s67, v246, 40
	v_ashrrev_i32_e32 v1, 31, v0
	v_mov_b64_e32 v[2:3], s[52:53]
	v_readlane_b32 s52, v246, 57
	v_readlane_b32 s66, v245, 7
	v_readlane_b32 s67, v245, 8
	v_readlane_b32 s62, v245, 3
	v_readlane_b32 s63, v245, 4
	v_readlane_b32 s64, v245, 5
	v_readlane_b32 s65, v245, 6
	v_mad_i64_i32 v[2:3], s[12:13], v0, s20, v[2:3]
	v_readlane_b32 s53, v246, 58
	v_readlane_b32 s54, v246, 59
	v_readlane_b32 s55, v246, 60
	v_readlane_b32 s56, v246, 61
	v_readlane_b32 s57, v246, 62
	v_readlane_b32 s58, v246, 63
	v_readlane_b32 s59, v245, 0
	v_readlane_b32 s60, v245, 1
	v_readlane_b32 s61, v245, 2
	s_add_i32 s11, s11, s90
	s_add_i32 s10, s10, s9
	s_cmpk_gt_i32 s11, 0x17f
	s_waitcnt vmcnt(8)
	v_fma_f32 v23, v18, v36, 0
	v_fmac_f32_e32 v23, v19, v37
	s_waitcnt vmcnt(0)
	v_fma_f32 v72, v52, v68, 0
	v_fmac_f32_e32 v23, v20, v38
	v_fmac_f32_e32 v72, v53, v69
	v_fmac_f32_e32 v23, v21, v39
	v_fmac_f32_e32 v72, v54, v70
	v_fmac_f32_e32 v23, v12, v32
	v_fmac_f32_e32 v72, v55, v71
	v_fmac_f32_e32 v23, v13, v33
	v_fmac_f32_e32 v72, v48, v64
	v_fmac_f32_e32 v23, v14, v34
	v_fmac_f32_e32 v72, v49, v65
	v_fmac_f32_e32 v23, v15, v35
	v_fmac_f32_e32 v72, v50, v66
	v_fmac_f32_e32 v23, v8, v28
	v_fmac_f32_e32 v72, v51, v67
	v_fmac_f32_e32 v23, v9, v29
	v_fmac_f32_e32 v72, v44, v60
	v_fmac_f32_e32 v23, v10, v30
	v_fmac_f32_e32 v72, v45, v61
	v_fmac_f32_e32 v23, v11, v31
	v_fmac_f32_e32 v72, v46, v62
	v_fmac_f32_e32 v23, v4, v24
	v_fmac_f32_e32 v72, v47, v63
	v_fmac_f32_e32 v23, v5, v25
	v_fmac_f32_e32 v72, v40, v56
	v_fmac_f32_e32 v23, v6, v26
	v_fmac_f32_e32 v72, v41, v57
	v_fmac_f32_e32 v23, v7, v27
	global_load_dwordx4 v[4:7], v137, s[0:1] offset:80
	global_load_dwordx4 v[8:11], v137, s[0:1] offset:64
	global_load_dwordx4 v[12:15], v137, s[0:1] offset:112
	global_load_dwordx4 v[18:21], v137, s[0:1] offset:96
	global_load_dwordx4 v[24:27], v137, s[0:1] offset:208
	global_load_dwordx4 v[28:31], v137, s[0:1] offset:192
	global_load_dwordx4 v[32:35], v137, s[0:1] offset:240
	global_load_dwordx4 v[36:39], v137, s[0:1] offset:224
	v_fmac_f32_e32 v72, v42, v58
	v_fmac_f32_e32 v72, v43, v59
	global_load_dwordx4 v[40:43], v137, s[0:1] offset:336
	global_load_dwordx4 v[44:47], v137, s[0:1] offset:320
	global_load_dwordx4 v[48:51], v137, s[0:1] offset:368
	global_load_dwordx4 v[52:55], v137, s[0:1] offset:352
	global_load_dwordx4 v[56:59], v137, s[0:1] offset:464
	global_load_dwordx4 v[60:63], v137, s[0:1] offset:448
	global_load_dwordx4 v[64:67], v137, s[0:1] offset:496
	global_load_dwordx4 v[68:71], v137, s[0:1] offset:480
	s_waitcnt vmcnt(10)
	v_fmac_f32_e32 v23, v8, v28
	v_fmac_f32_e32 v23, v9, v29
	v_fmac_f32_e32 v23, v10, v30
	s_waitcnt vmcnt(2)
	v_fmac_f32_e32 v72, v44, v60
	v_fmac_f32_e32 v72, v45, v61
	v_fmac_f32_e32 v23, v11, v31
	v_fmac_f32_e32 v72, v46, v62
	v_fmac_f32_e32 v23, v4, v24
	v_fmac_f32_e32 v72, v47, v63
	v_fmac_f32_e32 v23, v5, v25
	v_fmac_f32_e32 v72, v40, v56
	v_fmac_f32_e32 v23, v6, v26
	v_fmac_f32_e32 v72, v41, v57
	v_fmac_f32_e32 v23, v7, v27
	v_pk_mul_f32 v[4:5], v[18:19], v[36:37]
	v_fmac_f32_e32 v72, v42, v58
	v_add_f32_e32 v4, v23, v4
	v_fmac_f32_e32 v72, v43, v59
	v_add_f32_e32 v6, v4, v5
	s_waitcnt vmcnt(0)
	v_pk_mul_f32 v[4:5], v[52:53], v[68:69]
	v_lshlrev_b64 v[10:11], 9, v[0:1]
	v_add_f32_e32 v4, v72, v4
	v_add_f32_e32 v7, v4, v5
	v_pk_mul_f32 v[4:5], v[20:21], v[38:39]
	s_nop 0
	v_add_f32_e32 v4, v6, v4
	v_add_f32_e32 v6, v4, v5
	v_pk_mul_f32 v[4:5], v[54:55], v[70:71]
	s_nop 0
	v_add_f32_e32 v4, v7, v4
	v_add_f32_e32 v7, v4, v5
	v_pk_mul_f32 v[4:5], v[12:13], v[32:33]
	s_nop 0
	v_add_f32_e32 v4, v6, v4
	v_add_f32_e32 v6, v4, v5
	v_pk_mul_f32 v[4:5], v[48:49], v[64:65]
	s_nop 0
	v_add_f32_e32 v4, v7, v4
	v_add_f32_e32 v7, v4, v5
	v_pk_mul_f32 v[4:5], v[14:15], v[34:35]
	s_nop 0
	v_add_f32_e32 v4, v6, v4
	v_add_f32_e32 v6, v4, v5
	v_pk_mul_f32 v[4:5], v[50:51], v[66:67]
	v_cmp_ngt_f32_e32 vcc, s18, v6
	v_add_f32_e32 v4, v7, v4
	v_mul_f32_e32 v7, 0x3fb8aa3b, v6
	v_fma_f32 v8, v6, s17, -v7
	v_rndne_f32_e32 v9, v7
	v_fmac_f32_e32 v8, 0x32a5705f, v6
	v_sub_f32_e32 v7, v7, v9
	v_add_f32_e32 v7, v7, v8
	v_exp_f32_e32 v7, v7
	v_cvt_i32_f32_e32 v8, v9
	v_add_f32_e32 v4, v4, v5
	v_and_b32_e32 v5, 63, v16
	v_lshlrev_b32_e32 v136, 3, v5
	v_ldexp_f32 v7, v7, v8
	v_cndmask_b32_e32 v7, 0, v7, vcc
	v_cmp_nlt_f32_e32 vcc, s19, v6
	s_nop 1
	v_cndmask_b32_e32 v6, v185, v7, vcc
	v_mul_f32_e32 v7, 0x3fb8aa3b, v4
	v_fma_f32 v8, v4, s17, -v7
	v_rndne_f32_e32 v9, v7
	v_fmac_f32_e32 v8, 0x32a5705f, v4
	v_sub_f32_e32 v7, v7, v9
	v_add_f32_e32 v7, v7, v8
	v_exp_f32_e32 v7, v7
	v_cvt_i32_f32_e32 v8, v9
	v_cmp_ngt_f32_e32 vcc, s18, v4
	v_ldexp_f32 v7, v7, v8
	s_nop 0
	v_cndmask_b32_e32 v7, 0, v7, vcc
	v_cmp_nlt_f32_e32 vcc, s19, v4
	s_nop 1
	v_cndmask_b32_e32 v4, v185, v7, vcc
	v_sub_f32_e32 v4, v6, v4
	v_mov_b32_e32 v240, v4
	s_mov_b32 s98, 1
	s_branch fin_lam_join
fin_lam_skip:
	v_mov_b32_e32 v16, v139
	v_ashrrev_i32_e32 v0, 6, v16
	v_readlane_b32 s52, v246, 25
	v_add_u32_e32 v0, s10, v0
	v_readlane_b32 s53, v246, 26
	v_readlane_b32 s54, v246, 27
	v_readlane_b32 s55, v246, 28
	v_readlane_b32 s56, v246, 29
	v_readlane_b32 s57, v246, 30
	v_readlane_b32 s58, v246, 31
	v_readlane_b32 s59, v246, 32
	v_readlane_b32 s60, v246, 33
	v_readlane_b32 s61, v246, 34
	v_readlane_b32 s62, v246, 35
	v_readlane_b32 s63, v246, 36
	v_readlane_b32 s64, v246, 37
	v_readlane_b32 s65, v246, 38
	v_readlane_b32 s66, v246, 39
	v_readlane_b32 s67, v246, 40
	v_ashrrev_i32_e32 v1, 31, v0
	v_mov_b64_e32 v[2:3], s[52:53]
	v_readlane_b32 s52, v246, 57
	v_readlane_b32 s66, v245, 7
	v_readlane_b32 s67, v245, 8
	v_readlane_b32 s62, v245, 3
	v_readlane_b32 s63, v245, 4
	v_readlane_b32 s64, v245, 5
	v_readlane_b32 s65, v245, 6
	v_mad_i64_i32 v[2:3], s[12:13], v0, s20, v[2:3]
	v_readlane_b32 s53, v246, 58
	v_readlane_b32 s54, v246, 59
	v_readlane_b32 s55, v246, 60
	v_readlane_b32 s56, v246, 61
	v_readlane_b32 s57, v246, 62
	v_readlane_b32 s58, v246, 63
	v_readlane_b32 s59, v245, 0
	v_readlane_b32 s60, v245, 1
	v_readlane_b32 s61, v245, 2
	s_add_i32 s11, s11, s90
	s_add_i32 s10, s10, s9
	s_cmpk_gt_i32 s11, 0x17f
	v_lshlrev_b64 v[10:11], 9, v[0:1]
	s_nop 0
	s_nop 0
	s_nop 0
	s_nop 0
	s_nop 0
	v_and_b32_e32 v5, 63, v16
	v_lshlrev_b32_e32 v136, 3, v5
	s_nop 1
	s_nop 0
	s_nop 1
	v_mov_b32_e32 v4, v240
fin_lam_join:
	v_lshl_add_u64 v[6:7], s[66:67], 0, v[10:11]
	v_lshl_add_u64 v[8:9], v[6:7], 0, v[136:137]
	global_load_dwordx2 v[6:7], v[8:9], off
	v_add_co_u32_e32 v8, vcc, s21, v8
	v_add_f32_e32 v4, v17, v4
	s_nop 0
	v_addc_co_u32_e32 v9, vcc, 0, v9, vcc
	global_load_dwordx2 v[12:13], v[8:9], off
	v_cmp_lt_i32_e32 vcc, v184, v178
	s_waitcnt vmcnt(1)
	v_lshlrev_b32_e32 v14, 16, v7
	v_cndmask_b32_e32 v8, v176, v184, vcc
	v_cmp_lt_i32_e32 vcc, v183, v178
	v_lshlrev_b32_e32 v23, 2, v8
	v_and_b32_e32 v15, 0xffff0000, v7
	v_cndmask_b32_e32 v8, v176, v183, vcc
	v_cmp_lt_i32_e32 vcc, v182, v178
	v_lshlrev_b32_e32 v24, 2, v8
	s_waitcnt vmcnt(0)
	v_lshlrev_b32_e32 v28, 16, v13
	v_cndmask_b32_e32 v8, v176, v182, vcc
	v_cmp_lt_i32_e32 vcc, v181, v178
	v_lshlrev_b32_e32 v25, 2, v8
	v_and_b32_e32 v29, 0xffff0000, v13
	v_cndmask_b32_e32 v8, v176, v181, vcc
	v_lshlrev_b32_e32 v26, 2, v8
	v_lshlrev_b32_e32 v8, 4, v5
	v_and_b32_e32 v9, 0xf0, v8
	global_load_dwordx4 v[18:21], v9, s[2:3]
	v_lshlrev_b32_e32 v30, 16, v6
	v_and_b32_e32 v31, 0xffff0000, v6
	v_lshlrev_b32_e32 v6, 16, v12
	v_and_b32_e32 v7, 0xffff0000, v12
	v_pk_fma_f32 v[14:15], v[4:5], v[28:29], v[14:15] op_sel_hi:[0,1,1] neg_lo:[1,0,0] neg_hi:[1,0,0]
	v_pk_fma_f32 v[4:5], v[4:5], v[6:7], v[30:31] op_sel_hi:[0,1,1] neg_lo:[1,0,0] neg_hi:[1,0,0]
	v_pk_mul_f32 v[6:7], v[4:5], v[4:5]
	v_pk_mul_f32 v[28:29], v[14:15], v[14:15]
	v_add_f32_e32 v6, v6, v7
	v_add_f32_e32 v6, v28, v6
	v_add_f32_e32 v6, v29, v6
	ds_bpermute_b32 v7, v23, v6
	s_waitcnt lgkmcnt(0)
	v_add_f32_e32 v6, v6, v7
	ds_bpermute_b32 v7, v24, v6
	s_waitcnt lgkmcnt(0)
	v_add_f32_e32 v6, v6, v7
	ds_bpermute_b32 v7, v25, v6
	s_waitcnt lgkmcnt(0)
	v_add_f32_e32 v6, v6, v7
	ds_bpermute_b32 v7, v26, v6
	s_waitcnt lgkmcnt(0)
	v_add_f32_e32 v6, v6, v7
	v_fmamk_f32 v6, v6, 0x3c800000, v138
	v_cmp_gt_f32_e32 vcc, s33, v6
	v_mul_f32_e32 v7, 0x4b800000, v6
	s_nop 0
	v_cndmask_b32_e32 v6, v6, v7, vcc
	v_rsq_f32_e32 v6, v6
	s_nop 0
	v_mul_f32_e32 v7, 0x45800000, v6
	v_cndmask_b32_e32 v6, v6, v7, vcc
	v_mul_f32_e32 v6, v22, v6
	v_pk_mul_f32 v[4:5], v[4:5], v[6:7] op_sel_hi:[1,0]
	v_pk_mul_f32 v[6:7], v[14:15], v[6:7] op_sel_hi:[1,0]
	s_waitcnt vmcnt(0)
	v_pk_mul_f32 v[4:5], v[18:19], v[4:5]
	v_pk_mul_f32 v[6:7], v[20:21], v[6:7]
	v_cvt_pk_bf16_f32 v4, v4, v5
	v_cvt_pk_bf16_f32 v5, v6, v7
	v_mov_b64_e32 v[6:7], s[14:15]
	v_mad_i64_i32 v[6:7], s[12:13], v0, s36, v[6:7]
	v_lshl_add_u64 v[12:13], v[6:7], 0, v[136:137]
	global_store_dwordx2 v[12:13], v[4:5], off
	v_lshl_add_u64 v[4:5], s[62:63], 0, v[10:11]
	v_lshl_add_u64 v[4:5], v[4:5], 0, v[136:137]
	global_load_dwordx2 v[14:15], v[4:5], off
	v_lshl_add_u64 v[4:5], s[64:65], 0, v[10:11]
	v_lshl_add_u64 v[4:5], v[4:5], 0, v[136:137]
	v_lshl_add_u64 v[20:21], v[2:3], 0, v[136:137]
	global_load_dwordx2 v[18:19], v[4:5], off
	s_nop 0
	global_load_dwordx4 v[4:7], v9, s[4:5]
	global_load_dwordx2 v[2:3], v[20:21], off offset:3104
	v_readlane_b32 s52, v246, 41
	v_readlane_b32 s53, v246, 42
	v_readlane_b32 s54, v246, 43
	v_readlane_b32 s55, v246, 44
	v_lshl_add_u64 v[10:11], s[52:53], 0, v[10:11]
	v_lshl_add_u64 v[10:11], v[10:11], 0, v[136:137]
	v_readlane_b32 s56, v246, 45
	v_readlane_b32 s57, v246, 46
	v_readlane_b32 s58, v246, 47
	v_readlane_b32 s59, v246, 48
	v_readlane_b32 s60, v246, 49
	v_readlane_b32 s61, v246, 50
	v_readlane_b32 s62, v246, 51
	v_readlane_b32 s63, v246, 52
	v_readlane_b32 s64, v246, 53
	v_readlane_b32 s65, v246, 54
	v_readlane_b32 s66, v246, 55
	v_readlane_b32 s67, v246, 56
	s_waitcnt vmcnt(3)
	v_lshlrev_b32_e32 v28, 16, v15
	v_and_b32_e32 v29, 0xffff0000, v15
	v_lshlrev_b32_e32 v32, 16, v14
	v_and_b32_e32 v33, 0xffff0000, v14
	s_waitcnt vmcnt(2)
	v_lshlrev_b32_e32 v14, 16, v18
	v_and_b32_e32 v15, 0xffff0000, v18
	v_lshlrev_b32_e32 v30, 16, v19
	v_and_b32_e32 v31, 0xffff0000, v19
	v_pk_add_f32 v[14:15], v[32:33], v[14:15]
	s_waitcnt vmcnt(0)
	v_lshlrev_b32_e32 v32, 16, v2
	v_and_b32_e32 v33, 0xffff0000, v2
	v_pk_add_f32 v[28:29], v[28:29], v[30:31]
	v_lshlrev_b32_e32 v9, 16, v3
	v_and_b32_e32 v27, 0xffff0000, v3
	v_pk_mul_f32 v[18:19], v[14:15], v[14:15]
	v_mul_f32_e32 v2, 0xbfb8aa3b, v32
	v_mul_f32_e32 v3, 0xbfb8aa3b, v33
	v_pk_mul_f32 v[30:31], v[28:29], v[28:29]
	v_exp_f32_e32 v2, v2
	v_exp_f32_e32 v3, v3
	v_add_f32_e32 v18, v18, v19
	v_add_f32_e32 v18, v30, v18
	v_add_f32_e32 v18, v31, v18
	ds_bpermute_b32 v19, v23, v18
	v_pk_add_f32 v[2:3], v[2:3], 1.0 op_sel_hi:[1,0]
	s_waitcnt lgkmcnt(0)
	v_add_f32_e32 v18, v18, v19
	v_div_scale_f32 v34, s[12:13], v3, v3, v33
	v_rcp_f32_e32 v35, v34
	ds_bpermute_b32 v19, v24, v18
	v_fma_f32 v36, -v34, v35, 1.0
	v_fmac_f32_e32 v35, v36, v35
	v_div_scale_f32 v36, vcc, v33, v3, v33
	v_mul_f32_e32 v37, v36, v35
	v_fma_f32 v38, -v34, v37, v36
	v_fmac_f32_e32 v37, v38, v35
	s_waitcnt lgkmcnt(0)
	v_add_f32_e32 v18, v18, v19
	v_fma_f32 v34, -v34, v37, v36
	ds_bpermute_b32 v19, v25, v18
	v_div_fmas_f32 v34, v34, v35, v37
	v_div_fixup_f32 v3, v34, v3, v33
	v_div_scale_f32 v33, s[12:13], v2, v2, v32
	v_rcp_f32_e32 v34, v33
	s_waitcnt lgkmcnt(0)
	v_add_f32_e32 v18, v18, v19
	ds_bpermute_b32 v19, v26, v18
	v_fma_f32 v35, -v33, v34, 1.0
	v_fmac_f32_e32 v34, v35, v34
	v_div_scale_f32 v35, vcc, v32, v2, v32
	v_mul_f32_e32 v36, v35, v34
	v_fma_f32 v37, -v33, v36, v35
	v_fmac_f32_e32 v36, v37, v34
	s_waitcnt lgkmcnt(0)
	v_add_f32_e32 v18, v18, v19
	v_fma_f32 v33, -v33, v36, v35
	v_fmamk_f32 v18, v18, 0x3c800000, v138
	v_div_fmas_f32 v33, v33, v34, v36
	v_cmp_gt_f32_e32 vcc, s33, v18
	v_mul_f32_e32 v19, 0x4b800000, v18
	v_div_fixup_f32 v2, v33, v2, v32
	v_cndmask_b32_e32 v18, v18, v19, vcc
	v_rsq_f32_e32 v18, v18
	s_nop 0
	v_mul_f32_e32 v19, 0x45800000, v18
	v_cndmask_b32_e32 v18, v18, v19, vcc
	v_pk_mul_f32 v[14:15], v[14:15], v[18:19] op_sel_hi:[1,0]
	s_nop 0
	v_pk_mul_f32 v[4:5], v[4:5], v[14:15]
	v_pk_mul_f32 v[14:15], v[28:29], v[18:19] op_sel_hi:[1,0]
	v_pk_mul_f32 v[2:3], v[2:3], v[4:5]
	v_pk_mul_f32 v[6:7], v[6:7], v[14:15]
	v_cvt_pk_bf16_f32 v2, v2, v3
	v_mul_f32_e32 v3, 0xbfb8aa3b, v9
	v_exp_f32_e32 v4, v3
	v_mul_f32_e32 v3, 0xbfb8aa3b, v27
	v_exp_f32_e32 v5, v3
	s_nop 0
	v_pk_add_f32 v[4:5], v[4:5], 1.0 op_sel_hi:[1,0]
	s_nop 0
	v_div_scale_f32 v3, s[12:13], v5, v5, v27
	v_rcp_f32_e32 v14, v3
	s_nop 0
	v_fma_f32 v15, -v3, v14, 1.0
	v_fmac_f32_e32 v14, v15, v14
	v_div_scale_f32 v15, vcc, v27, v5, v27
	v_mul_f32_e32 v18, v15, v14
	v_fma_f32 v19, -v3, v18, v15
	v_fmac_f32_e32 v18, v19, v14
	v_fma_f32 v3, -v3, v18, v15
	v_div_fmas_f32 v3, v3, v14, v18
	v_div_fixup_f32 v5, v3, v5, v27
	v_div_scale_f32 v3, s[12:13], v4, v4, v9
	v_rcp_f32_e32 v14, v3
	s_nop 0
	v_fma_f32 v15, -v3, v14, 1.0
	v_fmac_f32_e32 v14, v15, v14
	v_div_scale_f32 v15, vcc, v9, v4, v9
	v_mul_f32_e32 v18, v15, v14
	v_fma_f32 v19, -v3, v18, v15
	v_fmac_f32_e32 v18, v19, v14
	v_fma_f32 v3, -v3, v18, v15
	v_div_fmas_f32 v3, v3, v14, v18
	v_div_fixup_f32 v4, v3, v4, v9
	v_pk_mul_f32 v[4:5], v[4:5], v[6:7]
	v_mov_b32_e32 v9, v137
	v_cvt_pk_bf16_f32 v3, v4, v5
	global_store_dwordx2 v[12:13], v[2:3], off offset:512
	v_lshlrev_b64 v[4:5], 10, v[0:1]
	global_load_dwordx2 v[18:19], v[10:11], off
	v_add_co_u32_e32 v10, vcc, s16, v20
	v_lshl_add_u64 v[0:1], s[24:25], 0, v[4:5]
	v_lshl_add_u64 v[4:5], s[26:27], 0, v[4:5]
	v_addc_co_u32_e32 v11, vcc, 0, v21, vcc
	v_lshl_add_u64 v[0:1], v[0:1], 0, v[8:9]
	v_lshl_add_u64 v[4:5], v[4:5], 0, v[8:9]
	global_load_dwordx2 v[14:15], v[10:11], off offset:352
	v_bfe_u32 v9, v16, 4, 2
	global_load_dwordx4 v[0:3], v[0:1], off
	v_or_b32_e32 v10, s8, v9
	global_load_dwordx4 v[4:7], v[4:5], off
	v_ashrrev_i32_e32 v11, 31, v10
	v_lshl_add_u64 v[10:11], v[10:11], 2, s[48:49]
	global_load_dword v16, v[10:11], off
	v_cmp_lt_i32_e32 vcc, v180, v178
	s_waitcnt vmcnt(4)
	v_lshlrev_b32_e32 v20, 16, v19
	v_and_b32_e32 v21, 0xffff0000, v19
	v_cndmask_b32_e32 v9, v176, v180, vcc
	v_lshlrev_b32_e32 v27, 2, v9
	global_load_dwordx4 v[8:11], v8, s[6:7]
	s_waitcnt vmcnt(4)
	v_lshlrev_b32_e32 v19, 16, v15
	v_and_b32_e32 v15, 0xffff0000, v15
	v_mul_f32_e32 v28, 0xbfb8aa3b, v19
	v_exp_f32_e32 v28, v28
	s_waitcnt vmcnt(2)
	v_pk_add_f32 v[0:1], v[0:1], v[4:5]
	v_mul_f32_e32 v4, 0xbfb8aa3b, v15
	v_exp_f32_e32 v29, v4
	v_pk_add_f32 v[2:3], v[2:3], v[6:7]
	v_pk_add_f32 v[4:5], v[28:29], 1.0 op_sel_hi:[1,0]
	s_nop 0
	v_div_scale_f32 v6, s[12:13], v5, v5, v15
	v_rcp_f32_e32 v7, v6
	s_waitcnt vmcnt(1)
	v_pk_fma_f32 v[2:3], v[16:17], v[20:21], v[2:3] op_sel_hi:[0,1,1]
	v_fma_f32 v20, -v6, v7, 1.0
	v_fmac_f32_e32 v7, v20, v7
	v_div_scale_f32 v20, vcc, v15, v5, v15
	v_mul_f32_e32 v21, v20, v7
	v_fma_f32 v28, -v6, v21, v20
	v_fmac_f32_e32 v21, v28, v7
	v_fma_f32 v6, -v6, v21, v20
	v_div_fmas_f32 v6, v6, v7, v21
	v_div_fixup_f32 v5, v6, v5, v15
	v_div_scale_f32 v6, s[12:13], v4, v4, v19
	v_rcp_f32_e32 v7, v6
	s_nop 0
	v_fma_f32 v15, -v6, v7, 1.0
	v_fmac_f32_e32 v7, v15, v7
	v_div_scale_f32 v15, vcc, v19, v4, v19
	v_mul_f32_e32 v20, v15, v7
	v_fma_f32 v21, -v6, v20, v15
	v_fmac_f32_e32 v20, v21, v7
	v_fma_f32 v6, -v6, v20, v15
	v_div_fmas_f32 v6, v6, v7, v20
	v_div_fixup_f32 v4, v6, v4, v19
	v_lshlrev_b32_e32 v6, 16, v18
	v_and_b32_e32 v7, 0xffff0000, v18
	v_lshlrev_b32_e32 v18, 16, v14
	v_and_b32_e32 v19, 0xffff0000, v14
	v_mul_f32_e32 v14, 0xbfb8aa3b, v18
	v_pk_fma_f32 v[0:1], v[16:17], v[6:7], v[0:1] op_sel_hi:[0,1,1]
	v_mul_f32_e32 v6, 0xbfb8aa3b, v19
	v_exp_f32_e32 v14, v14
	v_exp_f32_e32 v15, v6
	v_pk_mul_f32 v[2:3], v[2:3], v[4:5]
	v_pk_add_f32 v[6:7], v[14:15], 1.0 op_sel_hi:[1,0]
	s_nop 0
	v_div_scale_f32 v14, s[12:13], v7, v7, v19
	v_rcp_f32_e32 v15, v14
	v_pk_mul_f32 v[4:5], v[2:3], v[2:3]
	v_fma_f32 v16, -v14, v15, 1.0
	v_fmac_f32_e32 v15, v16, v15
	v_div_scale_f32 v16, vcc, v19, v7, v19
	v_mul_f32_e32 v20, v16, v15
	v_fma_f32 v21, -v14, v20, v16
	v_fmac_f32_e32 v20, v21, v15
	v_fma_f32 v14, -v14, v20, v16
	v_div_fmas_f32 v14, v14, v15, v20
	v_div_fixup_f32 v7, v14, v7, v19
	v_div_scale_f32 v14, s[12:13], v6, v6, v18
	v_rcp_f32_e32 v15, v14
	s_nop 0
	v_fma_f32 v16, -v14, v15, 1.0
	v_fmac_f32_e32 v15, v16, v15
	v_div_scale_f32 v16, vcc, v18, v6, v18
	v_mul_f32_e32 v19, v16, v15
	v_fma_f32 v20, -v14, v19, v16
	v_fmac_f32_e32 v19, v20, v15
	v_fma_f32 v14, -v14, v19, v16
	v_div_fmas_f32 v14, v14, v15, v19
	v_div_fixup_f32 v6, v14, v6, v18
	v_pk_mul_f32 v[0:1], v[0:1], v[6:7]
	s_nop 0
	v_pk_mul_f32 v[6:7], v[0:1], v[0:1]
	s_nop 0
	v_add_f32_e32 v6, v6, v7
	v_add_f32_e32 v4, v4, v6
	v_add_f32_e32 v4, v5, v4
	ds_bpermute_b32 v5, v23, v4
	s_waitcnt lgkmcnt(0)
	v_add_f32_e32 v4, v4, v5
	ds_bpermute_b32 v5, v24, v4
	s_waitcnt lgkmcnt(0)
	v_add_f32_e32 v4, v4, v5
	ds_bpermute_b32 v5, v25, v4
	s_waitcnt lgkmcnt(0)
	v_add_f32_e32 v4, v4, v5
	ds_bpermute_b32 v5, v26, v4
	s_waitcnt lgkmcnt(0)
	v_add_f32_e32 v4, v4, v5
	ds_bpermute_b32 v5, v27, v4
	s_waitcnt lgkmcnt(0)
	v_add_f32_e32 v4, v4, v5
	v_fmamk_f32 v4, v4, 0x3c000000, v138
	v_cmp_gt_f32_e32 vcc, s33, v4
	v_mul_f32_e32 v5, 0x4b800000, v4
	s_nop 0
	v_cndmask_b32_e32 v4, v4, v5, vcc
	v_rsq_f32_e32 v4, v4
	s_nop 0
	v_mul_f32_e32 v5, 0x45800000, v4
	v_cndmask_b32_e32 v4, v4, v5, vcc
	v_pk_mul_f32 v[0:1], v[0:1], v[4:5] op_sel_hi:[1,0]
	v_pk_mul_f32 v[2:3], v[2:3], v[4:5] op_sel_hi:[1,0]
	s_waitcnt vmcnt(0)
	v_pk_mul_f32 v[0:1], v[8:9], v[0:1]
	v_pk_mul_f32 v[2:3], v[10:11], v[2:3]
	v_cvt_pk_bf16_f32 v0, v0, v1
	v_cvt_pk_bf16_f32 v1, v2, v3
	global_store_dwordx2 v[12:13], v[0:1], off offset:1536
	s_cbranch_scc0 .LBB0_203
